# baseline (speedup 1.0000x reference)
.Lmy_rot_301:
	s_waitcnt lgkmcnt(6)
	v_mfma_f32_16x16x32_bf16 v[124:127], v[152:155], v[156:159], v[124:127]
	s_waitcnt lgkmcnt(5)
	s_mov_b32 m0, s63
	v_mfma_f32_16x16x32_bf16 v[120:123], v[160:163], v[156:159], v[120:123]
	global_load_lds_dwordx4 v146, s[72:73]
	s_waitcnt lgkmcnt(4)
	v_mfma_f32_16x16x32_bf16 v[108:111], v[152:155], v[164:167], v[108:111]
	v_mfma_f32_16x16x32_bf16 v[104:107], v[160:163], v[164:167], v[104:107]
	s_waitcnt lgkmcnt(3)
	s_mov_b32 m0, s51
	v_mfma_f32_16x16x32_bf16 v[116:119], v[168:171], v[156:159], v[116:119]
	global_load_lds_dwordx4 v128, s[70:71]
	v_mfma_f32_16x16x32_bf16 v[100:103], v[168:171], v[164:167], v[100:103]
	s_waitcnt lgkmcnt(2)
	v_mfma_f32_16x16x32_bf16 v[112:115], v[172:175], v[156:159], v[112:115]
	ds_read_b128 v[156:159], v189 offset:8192
	s_mov_b32 m0, s53
	v_mfma_f32_16x16x32_bf16 v[96:99], v[172:175], v[164:167], v[96:99]
	global_load_lds_dwordx4 v130, s[70:71]
	ds_read_b128 v[164:167], v189 offset:10240
	s_waitcnt lgkmcnt(3)
	v_mfma_f32_16x16x32_bf16 v[92:95], v[152:155], v[176:179], v[92:95]
	v_mfma_f32_16x16x32_bf16 v[88:91], v[160:163], v[176:179], v[88:91]
	s_mov_b32 m0, s55
	v_mfma_f32_16x16x32_bf16 v[84:87], v[168:171], v[176:179], v[84:87]
	global_load_lds_dwordx4 v132, s[70:71]
	v_mfma_f32_16x16x32_bf16 v[80:83], v[172:175], v[176:179], v[80:83]
	ds_read_b128 v[176:179], v189 offset:12288
	s_waitcnt lgkmcnt(3)
	v_mfma_f32_16x16x32_bf16 v[76:79], v[152:155], v[180:183], v[76:79]
	s_mov_b32 m0, s62
	v_mfma_f32_16x16x32_bf16 v[72:75], v[160:163], v[180:183], v[72:75]
	global_load_lds_dwordx4 v146, s[70:71]
	v_mfma_f32_16x16x32_bf16 v[68:71], v[168:171], v[180:183], v[68:71]
	v_mfma_f32_16x16x32_bf16 v[64:67], v[172:175], v[180:183], v[64:67]
	ds_read_b128 v[180:183], v189 offset:14336
	s_waitcnt lgkmcnt(3)
	v_mfma_f32_16x16x32_bf16 v[56:59], v[160:163], v[156:159], v[56:59]
	s_waitcnt lgkmcnt(2)
	v_mfma_f32_16x16x32_bf16 v[40:43], v[160:163], v[164:167], v[40:43]
	s_waitcnt lgkmcnt(1)
	v_mfma_f32_16x16x32_bf16 v[24:27], v[160:163], v[176:179], v[24:27]
	s_waitcnt lgkmcnt(0)
	v_mfma_f32_16x16x32_bf16 v[8:11], v[160:163], v[180:183], v[8:11]
	ds_read_b128 v[160:163], v151 offset:33792
	v_mfma_f32_16x16x32_bf16 v[60:63], v[152:155], v[156:159], v[60:63]
	v_mfma_f32_16x16x32_bf16 v[44:47], v[152:155], v[164:167], v[44:47]
	v_mfma_f32_16x16x32_bf16 v[28:31], v[152:155], v[176:179], v[28:31]
	v_mfma_f32_16x16x32_bf16 v[12:15], v[152:155], v[180:183], v[12:15]
	ds_read_b128 v[152:155], v189 offset:1024
	v_mfma_f32_16x16x32_bf16 v[36:39], v[168:171], v[164:167], v[36:39]
	v_mfma_f32_16x16x32_bf16 v[32:35], v[172:175], v[164:167], v[32:35]
	ds_read_b128 v[164:167], v151 offset:35840
	v_mfma_f32_16x16x32_bf16 v[52:55], v[168:171], v[156:159], v[52:55]
	v_mfma_f32_16x16x32_bf16 v[48:51], v[172:175], v[156:159], v[48:51]
	ds_read_b128 v[156:159], v189 offset:3072
	v_mfma_f32_16x16x32_bf16 v[20:23], v[168:171], v[176:179], v[20:23]
	v_mfma_f32_16x16x32_bf16 v[16:19], v[172:175], v[176:179], v[16:19]
	ds_read_b128 v[176:179], v189 offset:5120
	v_mfma_f32_16x16x32_bf16 v[4:7], v[168:171], v[180:183], v[4:7]
	ds_read_b128 v[168:171], v151 offset:37888
	v_mfma_f32_16x16x32_bf16 v[0:3], v[172:175], v[180:183], v[0:3]
	ds_read_b128 v[172:175], v151 offset:39936
	ds_read_b128 v[180:183], v189 offset:7168
	s_waitcnt lgkmcnt(6)
	v_mfma_f32_16x16x32_bf16 v[124:127], v[160:163], v[152:155], v[124:127]
	s_waitcnt lgkmcnt(5)
	v_mfma_f32_16x16x32_bf16 v[120:123], v[164:167], v[152:155], v[120:123]
	s_waitcnt lgkmcnt(4)
	v_mfma_f32_16x16x32_bf16 v[108:111], v[160:163], v[156:159], v[108:111]
	v_mfma_f32_16x16x32_bf16 v[104:107], v[164:167], v[156:159], v[104:107]
	s_waitcnt lgkmcnt(3)
	v_mfma_f32_16x16x32_bf16 v[92:95], v[160:163], v[176:179], v[92:95]
	v_mfma_f32_16x16x32_bf16 v[88:91], v[164:167], v[176:179], v[88:91]
	s_waitcnt lgkmcnt(2)
	v_mfma_f32_16x16x32_bf16 v[116:119], v[168:171], v[152:155], v[116:119]
	s_waitcnt lgkmcnt(1)
	v_mfma_f32_16x16x32_bf16 v[112:115], v[172:175], v[152:155], v[112:115]
	ds_read_b128 v[152:155], v189 offset:9216
	v_mfma_f32_16x16x32_bf16 v[100:103], v[168:171], v[156:159], v[100:103]
	v_mfma_f32_16x16x32_bf16 v[96:99], v[172:175], v[156:159], v[96:99]
	ds_read_b128 v[156:159], v189 offset:11264
	v_mfma_f32_16x16x32_bf16 v[84:87], v[168:171], v[176:179], v[84:87]
	v_mfma_f32_16x16x32_bf16 v[80:83], v[172:175], v[176:179], v[80:83]
	ds_read_b128 v[176:179], v189 offset:13312
	s_waitcnt lgkmcnt(3)
	v_mfma_f32_16x16x32_bf16 v[76:79], v[160:163], v[180:183], v[76:79]
	v_mfma_f32_16x16x32_bf16 v[72:75], v[164:167], v[180:183], v[72:75]
	v_mfma_f32_16x16x32_bf16 v[68:71], v[168:171], v[180:183], v[68:71]
	v_mfma_f32_16x16x32_bf16 v[64:67], v[172:175], v[180:183], v[64:67]
	ds_read_b128 v[180:183], v189 offset:15360
	s_waitcnt lgkmcnt(3)
	v_mfma_f32_16x16x32_bf16 v[60:63], v[160:163], v[152:155], v[60:63]
	v_mfma_f32_16x16x32_bf16 v[56:59], v[164:167], v[152:155], v[56:59]
	v_mfma_f32_16x16x32_bf16 v[52:55], v[168:171], v[152:155], v[52:55]
	v_mfma_f32_16x16x32_bf16 v[48:51], v[172:175], v[152:155], v[48:51]
	s_waitcnt lgkmcnt(2)
	v_mfma_f32_16x16x32_bf16 v[44:47], v[160:163], v[156:159], v[44:47]
	v_mfma_f32_16x16x32_bf16 v[40:43], v[164:167], v[156:159], v[40:43]
	v_mfma_f32_16x16x32_bf16 v[36:39], v[168:171], v[156:159], v[36:39]
	v_mfma_f32_16x16x32_bf16 v[32:35], v[172:175], v[156:159], v[32:35]
	s_add_u32 s69, s69, 0x1b900100
	s_addc_u32 s70, s74, 0
	s_add_u32 s72, s75, 0x100
	s_addc_u32 s73, s76, 0
	s_cmp_lt_u32 s68, 31
	s_cselect_b32 s71, s70, s31
	s_cselect_b32 s70, s69, s30
	s_waitcnt vmcnt(0)
	s_waitcnt lgkmcnt(0)
	s_barrier
	s_cselect_b32 s73, s73, s35
	s_cselect_b32 s72, s72, s34
	ds_read_b128 v[152:155], v150
	v_add_u32_e32 v151, v145, v136
	ds_read_b128 v[156:159], v151
	s_mov_b32 m0, s44
	v_mfma_f32_16x16x32_bf16 v[28:31], v[160:163], v[176:179], v[28:31]
	global_load_lds_dwordx4 v128, s[72:73]
	v_mfma_f32_16x16x32_bf16 v[12:15], v[160:163], v[180:183], v[12:15]
	ds_read_b128 v[160:163], v150 offset:2048
	v_mfma_f32_16x16x32_bf16 v[24:27], v[164:167], v[176:179], v[24:27]
	s_mov_b32 m0, s46
	v_mfma_f32_16x16x32_bf16 v[8:11], v[164:167], v[180:183], v[8:11]
	global_load_lds_dwordx4 v130, s[72:73]
	v_add_u32_e32 v151, v145, v137
	ds_read_b128 v[164:167], v151
	v_mfma_f32_16x16x32_bf16 v[20:23], v[168:171], v[176:179], v[20:23]
	v_mfma_f32_16x16x32_bf16 v[4:7], v[168:171], v[180:183], v[4:7]
	ds_read_b128 v[168:171], v150 offset:4096
	s_mov_b32 m0, s48
	v_mfma_f32_16x16x32_bf16 v[16:19], v[172:175], v[176:179], v[16:19]
	global_load_lds_dwordx4 v132, s[72:73]
	v_mfma_f32_16x16x32_bf16 v[0:3], v[172:175], v[180:183], v[0:3]
	ds_read_b128 v[172:175], v150 offset:6144
	v_add_u32_e32 v151, v145, v138
	ds_read_b128 v[176:179], v151
	v_add_u32_e32 v151, v145, v139
	ds_read_b128 v[180:183], v151
	s_waitcnt lgkmcnt(6)
	v_mfma_f32_16x16x32_bf16 v[124:127], v[152:155], v[156:159], v[124:127]
	s_waitcnt lgkmcnt(5)
	s_mov_b32 m0, s50
	v_mfma_f32_16x16x32_bf16 v[120:123], v[160:163], v[156:159], v[120:123]
	global_load_lds_dwordx4 v146, s[72:73]
	s_waitcnt lgkmcnt(4)
	v_mfma_f32_16x16x32_bf16 v[108:111], v[152:155], v[164:167], v[108:111]
	v_mfma_f32_16x16x32_bf16 v[104:107], v[160:163], v[164:167], v[104:107]
	s_waitcnt lgkmcnt(3)
	s_mov_b32 m0, s1
	v_mfma_f32_16x16x32_bf16 v[116:119], v[168:171], v[156:159], v[116:119]
	global_load_lds_dwordx4 v128, s[70:71]
	v_mfma_f32_16x16x32_bf16 v[100:103], v[168:171], v[164:167], v[100:103]
	s_waitcnt lgkmcnt(2)
	v_mfma_f32_16x16x32_bf16 v[112:115], v[172:175], v[156:159], v[112:115]
	v_add_u32_e32 v151, v145, v140
	ds_read_b128 v[156:159], v151
	s_mov_b32 m0, s45
	v_mfma_f32_16x16x32_bf16 v[96:99], v[172:175], v[164:167], v[96:99]
	global_load_lds_dwordx4 v130, s[70:71]
	v_add_u32_e32 v151, v145, v141
	ds_read_b128 v[164:167], v151
	s_waitcnt lgkmcnt(3)
	v_mfma_f32_16x16x32_bf16 v[92:95], v[152:155], v[176:179], v[92:95]
	v_mfma_f32_16x16x32_bf16 v[88:91], v[160:163], v[176:179], v[88:91]
	s_mov_b32 m0, s47
	v_mfma_f32_16x16x32_bf16 v[84:87], v[168:171], v[176:179], v[84:87]
	global_load_lds_dwordx4 v132, s[70:71]
	v_mfma_f32_16x16x32_bf16 v[80:83], v[172:175], v[176:179], v[80:83]
	v_add_u32_e32 v151, v145, v142
	ds_read_b128 v[176:179], v151
	s_waitcnt lgkmcnt(3)
	v_mfma_f32_16x16x32_bf16 v[76:79], v[152:155], v[180:183], v[76:79]
	s_mov_b32 m0, s49
	v_mfma_f32_16x16x32_bf16 v[72:75], v[160:163], v[180:183], v[72:75]
	global_load_lds_dwordx4 v146, s[70:71]
	v_mfma_f32_16x16x32_bf16 v[68:71], v[168:171], v[180:183], v[68:71]
	v_mfma_f32_16x16x32_bf16 v[64:67], v[172:175], v[180:183], v[64:67]
	v_add_u32_e32 v151, v145, v143
	ds_read_b128 v[180:183], v151
	s_waitcnt lgkmcnt(3)
	v_mfma_f32_16x16x32_bf16 v[56:59], v[160:163], v[156:159], v[56:59]
	s_waitcnt lgkmcnt(2)
	v_mfma_f32_16x16x32_bf16 v[40:43], v[160:163], v[164:167], v[40:43]
	s_waitcnt lgkmcnt(1)
	v_mfma_f32_16x16x32_bf16 v[24:27], v[160:163], v[176:179], v[24:27]
	s_waitcnt lgkmcnt(0)
	v_mfma_f32_16x16x32_bf16 v[8:11], v[160:163], v[180:183], v[8:11]
	ds_read_b128 v[160:163], v150 offset:1024
	v_mfma_f32_16x16x32_bf16 v[60:63], v[152:155], v[156:159], v[60:63]
	v_mfma_f32_16x16x32_bf16 v[44:47], v[152:155], v[164:167], v[44:47]
	v_mfma_f32_16x16x32_bf16 v[28:31], v[152:155], v[176:179], v[28:31]
	v_mfma_f32_16x16x32_bf16 v[12:15], v[152:155], v[180:183], v[12:15]
	v_add_u32_e32 v151, v149, v136
	ds_read_b128 v[152:155], v151
	v_mfma_f32_16x16x32_bf16 v[36:39], v[168:171], v[164:167], v[36:39]
	v_mfma_f32_16x16x32_bf16 v[32:35], v[172:175], v[164:167], v[32:35]
	ds_read_b128 v[164:167], v150 offset:3072
	v_mfma_f32_16x16x32_bf16 v[52:55], v[168:171], v[156:159], v[52:55]
	v_mfma_f32_16x16x32_bf16 v[48:51], v[172:175], v[156:159], v[48:51]
	v_add_u32_e32 v151, v149, v137
	ds_read_b128 v[156:159], v151
	v_mfma_f32_16x16x32_bf16 v[20:23], v[168:171], v[176:179], v[20:23]
	v_mfma_f32_16x16x32_bf16 v[16:19], v[172:175], v[176:179], v[16:19]
	v_add_u32_e32 v151, v149, v138
	ds_read_b128 v[176:179], v151
	v_mfma_f32_16x16x32_bf16 v[4:7], v[168:171], v[180:183], v[4:7]
	ds_read_b128 v[168:171], v150 offset:5120
	v_mfma_f32_16x16x32_bf16 v[0:3], v[172:175], v[180:183], v[0:3]
	ds_read_b128 v[172:175], v150 offset:7168
	v_add_u32_e32 v151, v149, v139
	ds_read_b128 v[180:183], v151
	s_waitcnt lgkmcnt(6)
	v_mfma_f32_16x16x32_bf16 v[124:127], v[160:163], v[152:155], v[124:127]
	s_waitcnt lgkmcnt(5)
	v_mfma_f32_16x16x32_bf16 v[120:123], v[164:167], v[152:155], v[120:123]
	s_waitcnt lgkmcnt(4)
	v_mfma_f32_16x16x32_bf16 v[108:111], v[160:163], v[156:159], v[108:111]
	v_mfma_f32_16x16x32_bf16 v[104:107], v[164:167], v[156:159], v[104:107]
	s_waitcnt lgkmcnt(3)
	v_mfma_f32_16x16x32_bf16 v[92:95], v[160:163], v[176:179], v[92:95]
	v_mfma_f32_16x16x32_bf16 v[88:91], v[164:167], v[176:179], v[88:91]
	s_waitcnt lgkmcnt(2)
	v_mfma_f32_16x16x32_bf16 v[116:119], v[168:171], v[152:155], v[116:119]
	s_waitcnt lgkmcnt(1)
	v_mfma_f32_16x16x32_bf16 v[112:115], v[172:175], v[152:155], v[112:115]
	v_add_u32_e32 v151, v149, v140
	ds_read_b128 v[152:155], v151
	v_mfma_f32_16x16x32_bf16 v[100:103], v[168:171], v[156:159], v[100:103]
	v_mfma_f32_16x16x32_bf16 v[96:99], v[172:175], v[156:159], v[96:99]
	v_add_u32_e32 v151, v149, v141
	ds_read_b128 v[156:159], v151
	v_mfma_f32_16x16x32_bf16 v[84:87], v[168:171], v[176:179], v[84:87]
	v_mfma_f32_16x16x32_bf16 v[80:83], v[172:175], v[176:179], v[80:83]
	v_add_u32_e32 v151, v149, v142
	ds_read_b128 v[176:179], v151
	s_waitcnt lgkmcnt(3)
	v_mfma_f32_16x16x32_bf16 v[76:79], v[160:163], v[180:183], v[76:79]
	v_mfma_f32_16x16x32_bf16 v[72:75], v[164:167], v[180:183], v[72:75]
	v_mfma_f32_16x16x32_bf16 v[68:71], v[168:171], v[180:183], v[68:71]
	v_mfma_f32_16x16x32_bf16 v[64:67], v[172:175], v[180:183], v[64:67]
	v_add_u32_e32 v151, v149, v143
	ds_read_b128 v[180:183], v151
	s_waitcnt lgkmcnt(3)
	v_mfma_f32_16x16x32_bf16 v[60:63], v[160:163], v[152:155], v[60:63]
	v_mfma_f32_16x16x32_bf16 v[56:59], v[164:167], v[152:155], v[56:59]
	v_mfma_f32_16x16x32_bf16 v[52:55], v[168:171], v[152:155], v[52:55]
	v_mfma_f32_16x16x32_bf16 v[48:51], v[172:175], v[152:155], v[48:51]
	s_waitcnt lgkmcnt(2)
	v_mfma_f32_16x16x32_bf16 v[44:47], v[160:163], v[156:159], v[44:47]
	v_mfma_f32_16x16x32_bf16 v[40:43], v[164:167], v[156:159], v[40:43]
	v_mfma_f32_16x16x32_bf16 v[36:39], v[168:171], v[156:159], v[36:39]
	v_mfma_f32_16x16x32_bf16 v[32:35], v[172:175], v[156:159], v[32:35]
	s_waitcnt vmcnt(0)
	s_add_u32 s4, s4, 0x100
	s_addc_u32 s5, s5, 0
	s_add_i32 s68, s68, 2
	s_cmpk_lg_i32 s4, 0x1000
	s_waitcnt lgkmcnt(0)
	s_barrier
	s_cbranch_scc1 .LBB0_301
	v_mfma_f32_16x16x32_bf16 v[28:31], v[160:163], v[176:179], v[28:31]
	v_mfma_f32_16x16x32_bf16 v[12:15], v[160:163], v[180:183], v[12:15]
	v_mfma_f32_16x16x32_bf16 v[24:27], v[164:167], v[176:179], v[24:27]
	v_mfma_f32_16x16x32_bf16 v[8:11], v[164:167], v[180:183], v[8:11]
	v_mfma_f32_16x16x32_bf16 v[20:23], v[168:171], v[176:179], v[20:23]
	v_mfma_f32_16x16x32_bf16 v[4:7], v[168:171], v[180:183], v[4:7]
	v_mfma_f32_16x16x32_bf16 v[16:19], v[172:175], v[176:179], v[16:19]
	v_mfma_f32_16x16x32_bf16 v[0:3], v[172:175], v[180:183], v[0:3]
	s_nop 15
	s_nop 15
	v_mov_b32_e32 v128, v184
	s_movk_i32 s1, 0xff80
	v_and_b32_e32 v129, 15, v128
	v_ashrrev_i32_e32 v130, 1, v128
	s_lshl_b32 s34, s0, 8
	v_and_or_b32 v163, v130, s1, v129
	s_cmp_lt_i32 s0, 8
	v_lshl_add_u32 v162, v163, 2, v202
	v_and_b32_e32 v164, 0xc0, v128
	s_cselect_b64 s[2:3], -1, 0
	s_cmp_lt_i32 s0, 10
	v_lshrrev_b32_e32 v128, 2, v128
	ds_read_b32 v150, v162
	s_cselect_b64 s[30:31], -1, 0
	s_add_i32 s1, s34, 0xfffff800
	v_and_b32_e32 v145, 12, v128
	v_or_b32_e32 v128, s34, v164
	v_ashrrev_i32_e32 v129, 31, v128
	v_or_b32_e32 v138, s1, v164
	v_add_u32_e32 v142, s43, v163
	s_cmp_gt_i32 s0, 9
	v_lshl_add_u64 v[140:141], v[128:129], 1, s[18:19]
	v_ashrrev_i32_e32 v128, 6, v138
	v_and_b32_e32 v165, 0xf8f, v142
	v_ashrrev_i32_e32 v168, 12, v142
	s_movk_i32 s0, 0xf7f
	v_ashrrev_i32_e32 v139, 31, v138
	v_add_u32_e32 v149, 0xffff8400, v128
	s_mov_b64 s[4:5], -1
	v_cmp_lt_u32_e64 s[0:1], s0, v165
	v_lshlrev_b32_e32 v166, 10, v168
	v_lshlrev_b32_e32 v167, 3, v165
	v_lshlrev_b32_e32 v136, 2, v145
	v_readlane_b32 s68, v253, 18
	s_cbranch_scc1 .LBB0_316
	v_lshlrev_b32_e32 v146, 7, v165
	v_lshl_add_u64 v[128:129], s[6:7], 0, v[146:147]
	v_mov_b32_e32 v137, v147
	v_lshl_add_u64 v[130:131], s[12:13], 0, v[146:147]
	v_lshl_add_u64 v[154:155], v[128:129], 0, v[136:137]
	v_lshl_add_u64 v[156:157], v[130:131], 0, v[136:137]
	v_add_u32_e32 v250, v146, v136
	global_load_dwordx4 v[214:217], v250, s[6:7] offset:0
	global_load_dwordx4 v[218:221], v250, s[12:13] offset:0
	global_load_dwordx4 v[222:225], v250, s[6:7] offset:64
	global_load_dwordx4 v[226:229], v250, s[12:13] offset:64
	global_load_dwordx4 v[230:233], v250, s[6:7] offset:2048
	global_load_dwordx4 v[234:237], v250, s[12:13] offset:2048
	global_load_dwordx4 v[238:241], v250, s[6:7] offset:2112
	global_load_dwordx4 v[242:245], v250, s[12:13] offset:2112
	v_ashrrev_i32_e32 v143, 31, v142
	v_lshlrev_b64 v[132:133], 12, v[142:143]
	s_waitcnt lgkmcnt(0)
	v_pk_mul_f32 v[170:171], v[116:117], v[150:151] op_sel_hi:[1,0]
	v_lshl_add_u64 v[152:153], v[140:141], 0, v[132:133]
	v_pk_mul_f32 v[134:135], v[124:125], v[150:151] op_sel_hi:[1,0]
	s_and_b64 vcc, exec, s[2:3]
	s_waitcnt vmcnt(6)
	v_mov_b32_e32 v128, v214
	v_mov_b32_e32 v129, v215
	v_mov_b32_e32 v130, v216
	v_mov_b32_e32 v131, v217
	v_mov_b32_e32 v158, v218
	v_mov_b32_e32 v159, v219
	v_mov_b32_e32 v160, v220
	v_mov_b32_e32 v161, v221
	v_add_u32_e32 v251, 0x1000, v250
	global_load_dwordx4 v[214:217], v251, s[6:7] offset:0
	global_load_dwordx4 v[218:221], v251, s[12:13] offset:0
	v_pk_mul_f32 v[132:133], v[170:171], v[158:159]
	s_nop 0
	v_pk_fma_f32 v[132:133], v[134:135], v[128:129], v[132:133] neg_lo:[0,0,1] neg_hi:[0,0,1]
	v_pk_mul_f32 v[134:135], v[134:135], v[158:159]
	v_pk_mul_f32 v[158:159], v[126:127], v[150:151] op_sel_hi:[1,0]
	v_pk_fma_f32 v[128:129], v[170:171], v[128:129], v[134:135]
	v_pk_mul_f32 v[170:171], v[118:119], v[150:151] op_sel_hi:[1,0]
	s_nop 0
	v_pk_mul_f32 v[134:135], v[170:171], v[160:161]
	s_nop 0
	v_pk_fma_f32 v[134:135], v[158:159], v[130:131], v[134:135] neg_lo:[0,0,1] neg_hi:[0,0,1]
	v_pk_mul_f32 v[158:159], v[158:159], v[160:161]
	s_nop 0
	v_pk_fma_f32 v[130:131], v[170:171], v[130:131], v[158:159]
	s_cbranch_vccz .LBB0_305
	s_mov_b32 s4, 0x3e000000
	v_lshlrev_b32_e32 v146, 1, v145
	v_pk_mul_f32 v[160:161], v[132:133], s[4:5] op_sel_hi:[1,0]
	v_pk_mul_f32 v[170:171], v[134:135], s[4:5] op_sel_hi:[1,0]
	v_lshl_add_u64 v[158:159], v[152:153], 0, v[146:147]
	v_cvt_pk_bf16_f32 v160, v160, v161
	v_cvt_pk_bf16_f32 v161, v170, v171
	global_store_dwordx2 v[158:159], v[160:161], off
	v_pk_mul_f32 v[160:161], v[128:129], s[4:5] op_sel_hi:[1,0]
	v_pk_mul_f32 v[170:171], v[130:131], s[4:5] op_sel_hi:[1,0]
	v_cvt_pk_bf16_f32 v160, v160, v161
	v_cvt_pk_bf16_f32 v161, v170, v171
	s_mov_b64 s[4:5], 0
	global_store_dwordx2 v[158:159], v[160:161], off offset:64

.LBB0_309:
	s_nop 0
	v_mov_b32_e32 v151, v150
	v_pk_mul_f32 v[132:133], v[120:121], v[150:151]
	v_pk_mul_f32 v[134:135], v[112:113], v[150:151]
	v_pk_mul_f32 v[170:171], v[122:123], v[150:151]
	v_pk_mul_f32 v[172:173], v[114:115], v[150:151]
	s_andn2_b64 vcc, exec, s[2:3]
	s_mov_b64 s[4:5], -1
	s_waitcnt vmcnt(6)
	v_mov_b32_e32 v154, v222
	v_mov_b32_e32 v155, v223
	v_mov_b32_e32 v156, v224
	v_mov_b32_e32 v157, v225
	v_mov_b32_e32 v128, v226
	v_mov_b32_e32 v129, v227
	v_mov_b32_e32 v130, v228
	v_mov_b32_e32 v131, v229
	v_add_u32_e32 v251, 0x1000, v250
	global_load_dwordx4 v[222:225], v251, s[6:7] offset:64
	global_load_dwordx4 v[226:229], v251, s[12:13] offset:64
	v_pk_mul_f32 v[174:175], v[134:135], v[128:129]
	v_pk_mul_f32 v[128:129], v[132:133], v[128:129]
	v_pk_mul_f32 v[176:177], v[172:173], v[130:131]
	v_pk_mul_f32 v[130:131], v[170:171], v[130:131]
	v_pk_fma_f32 v[132:133], v[132:133], v[154:155], v[174:175] neg_lo:[0,0,1] neg_hi:[0,0,1]
	v_pk_fma_f32 v[128:129], v[134:135], v[154:155], v[128:129]
	v_pk_fma_f32 v[134:135], v[170:171], v[156:157], v[176:177] neg_lo:[0,0,1] neg_hi:[0,0,1]
	v_pk_fma_f32 v[130:131], v[172:173], v[156:157], v[130:131]
	s_cbranch_vccnz .LBB0_311
	s_mov_b32 s4, 0x3e000000
	v_lshlrev_b32_e32 v146, 1, v145
	v_pk_mul_f32 v[154:155], v[132:133], s[4:5] op_sel_hi:[1,0]
	v_pk_mul_f32 v[156:157], v[134:135], s[4:5] op_sel_hi:[1,0]
	v_lshl_add_u64 v[152:153], v[152:153], 0, v[146:147]
	v_cvt_pk_bf16_f32 v154, v154, v155
	v_cvt_pk_bf16_f32 v155, v156, v157
	global_store_dwordx2 v[152:153], v[154:155], off offset:32
	v_pk_mul_f32 v[154:155], v[128:129], s[4:5] op_sel_hi:[1,0]
	v_pk_mul_f32 v[156:157], v[130:131], s[4:5] op_sel_hi:[1,0]
	v_cvt_pk_bf16_f32 v154, v154, v155
	v_cvt_pk_bf16_f32 v155, v156, v157
	s_mov_b64 s[4:5], 0
	global_store_dwordx2 v[152:153], v[154:155], off offset:96

.LBB0_326:
	ds_read_b32 v120, v162 offset:64
	v_add3_u32 v124, s43, v163, 16
	v_cndmask_b32_e64 v112, 0, 1, s[30:31]
	v_and_b32_e32 v132, 0xf9f, v124
	v_ashrrev_i32_e32 v133, 12, v124
	v_cmp_ne_u32_e64 s[4:5], 1, v112
	s_movk_i32 s0, 0xf7f
	v_cndmask_b32_e64 v112, 0, 1, s[2:3]
	s_mov_b64 s[34:35], -1
	s_andn2_b64 vcc, exec, s[30:31]
	v_cmp_lt_u32_e64 s[0:1], s0, v132
	v_lshlrev_b32_e32 v143, 10, v133
	s_waitcnt lgkmcnt(1)
	v_lshlrev_b32_e32 v150, 3, v132
	v_cmp_ne_u32_e64 s[2:3], 1, v112
	v_readlane_b32 s75, v253, 20
	s_cbranch_vccnz .LBB0_340
	v_lshlrev_b32_e32 v146, 7, v132
	v_lshl_add_u64 v[112:113], s[6:7], 0, v[146:147]
	v_mov_b32_e32 v137, v147
	v_lshl_add_u64 v[114:115], s[12:13], 0, v[146:147]
	v_lshl_add_u64 v[130:131], v[112:113], 0, v[136:137]
	v_lshl_add_u64 v[128:129], v[114:115], 0, v[136:137]
	v_ashrrev_i32_e32 v125, 31, v124
	v_lshlrev_b64 v[116:117], 12, v[124:125]
	s_waitcnt lgkmcnt(0)
	v_pk_mul_f32 v[126:127], v[100:101], v[120:121] op_sel_hi:[1,0]
	v_lshl_add_u64 v[122:123], v[140:141], 0, v[116:117]
	v_pk_mul_f32 v[118:119], v[108:109], v[120:121] op_sel_hi:[1,0]
	s_mov_b64 s[30:31], -1
	s_and_b64 vcc, exec, s[2:3]
	s_waitcnt vmcnt(6)
	v_mov_b32_e32 v112, v230
	v_mov_b32_e32 v113, v231
	v_mov_b32_e32 v114, v232
	v_mov_b32_e32 v115, v233
	v_mov_b32_e32 v152, v234
	v_mov_b32_e32 v153, v235
	v_mov_b32_e32 v154, v236
	v_mov_b32_e32 v155, v237
	v_add_u32_e32 v251, 0x1800, v250
	global_load_dwordx4 v[230:233], v251, s[6:7] offset:0
	global_load_dwordx4 v[234:237], v251, s[12:13] offset:0
	v_pk_mul_f32 v[116:117], v[126:127], v[152:153]
	s_nop 0
	v_pk_fma_f32 v[116:117], v[118:119], v[112:113], v[116:117] neg_lo:[0,0,1] neg_hi:[0,0,1]
	v_pk_mul_f32 v[118:119], v[118:119], v[152:153]
	v_pk_mul_f32 v[152:153], v[102:103], v[120:121] op_sel_hi:[1,0]
	v_pk_fma_f32 v[112:113], v[126:127], v[112:113], v[118:119]
	v_pk_mul_f32 v[126:127], v[110:111], v[120:121] op_sel_hi:[1,0]
	v_pk_mul_f32 v[118:119], v[152:153], v[154:155]
	s_nop 0
	v_pk_fma_f32 v[118:119], v[126:127], v[114:115], v[118:119] neg_lo:[0,0,1] neg_hi:[0,0,1]
	v_pk_mul_f32 v[126:127], v[126:127], v[154:155]
	s_nop 0
	v_pk_fma_f32 v[114:115], v[152:153], v[114:115], v[126:127]
	s_cbranch_vccnz .LBB0_329
	s_mov_b32 s30, 0x3e000000
	v_lshlrev_b32_e32 v146, 1, v145
	v_pk_mul_f32 v[152:153], v[116:117], s[30:31] op_sel_hi:[1,0]
	v_pk_mul_f32 v[154:155], v[118:119], s[30:31] op_sel_hi:[1,0]
	v_lshl_add_u64 v[126:127], v[122:123], 0, v[146:147]
	v_cvt_pk_bf16_f32 v152, v152, v153
	v_cvt_pk_bf16_f32 v153, v154, v155
	global_store_dwordx2 v[126:127], v[152:153], off
	v_pk_mul_f32 v[152:153], v[112:113], s[30:31] op_sel_hi:[1,0]
	v_pk_mul_f32 v[154:155], v[114:115], s[30:31] op_sel_hi:[1,0]
	v_cvt_pk_bf16_f32 v152, v152, v153
	v_cvt_pk_bf16_f32 v153, v154, v155
	s_mov_b64 s[30:31], 0
	global_store_dwordx2 v[126:127], v[152:153], off offset:64

.LBB0_333:
	s_nop 0
	v_mov_b32_e32 v121, v120
	v_pk_mul_f32 v[152:153], v[96:97], v[120:121]
	v_pk_mul_f32 v[118:119], v[104:105], v[120:121]
	s_mov_b64 s[30:31], -1
	s_and_b64 vcc, exec, s[2:3]
	s_waitcnt vmcnt(6)
	v_mov_b32_e32 v112, v238
	v_mov_b32_e32 v113, v239
	v_mov_b32_e32 v114, v240
	v_mov_b32_e32 v115, v241
	v_mov_b32_e32 v128, v242
	v_mov_b32_e32 v129, v243
	v_mov_b32_e32 v130, v244
	v_mov_b32_e32 v131, v245
	v_add_u32_e32 v251, 0x1800, v250
	global_load_dwordx4 v[238:241], v251, s[6:7] offset:64
	global_load_dwordx4 v[242:245], v251, s[12:13] offset:64
	v_pk_mul_f32 v[116:117], v[152:153], v[128:129]
	s_nop 0
	v_pk_fma_f32 v[116:117], v[118:119], v[112:113], v[116:117] neg_lo:[0,0,1] neg_hi:[0,0,1]
	v_pk_mul_f32 v[118:119], v[118:119], v[128:129]
	v_pk_mul_f32 v[128:129], v[106:107], v[120:121]
	v_pk_fma_f32 v[112:113], v[152:153], v[112:113], v[118:119]
	v_pk_mul_f32 v[152:153], v[98:99], v[120:121]
	s_nop 0
	v_pk_mul_f32 v[118:119], v[152:153], v[130:131]
	s_nop 0
	v_pk_fma_f32 v[118:119], v[128:129], v[114:115], v[118:119] neg_lo:[0,0,1] neg_hi:[0,0,1]
	v_pk_mul_f32 v[128:129], v[128:129], v[130:131]
	s_nop 0
	v_pk_fma_f32 v[114:115], v[152:153], v[114:115], v[128:129]
	s_cbranch_vccnz .LBB0_335
	s_mov_b32 s30, 0x3e000000
	v_lshlrev_b32_e32 v146, 1, v145
	v_pk_mul_f32 v[128:129], v[116:117], s[30:31] op_sel_hi:[1,0]
	v_pk_mul_f32 v[130:131], v[118:119], s[30:31] op_sel_hi:[1,0]
	v_lshl_add_u64 v[122:123], v[122:123], 0, v[146:147]
	v_cvt_pk_bf16_f32 v128, v128, v129
	v_cvt_pk_bf16_f32 v129, v130, v131
	global_store_dwordx2 v[122:123], v[128:129], off offset:32
	v_pk_mul_f32 v[128:129], v[112:113], s[30:31] op_sel_hi:[1,0]
	v_pk_mul_f32 v[130:131], v[114:115], s[30:31] op_sel_hi:[1,0]
	v_cvt_pk_bf16_f32 v128, v128, v129
	v_cvt_pk_bf16_f32 v129, v130, v131
	s_mov_b64 s[30:31], 0
	global_store_dwordx2 v[122:123], v[128:129], off offset:96

.LBB0_350:
	ds_read_b32 v104, v162 offset:128
	v_add3_u32 v108, s43, v163, 32
	v_and_b32_e32 v116, 0xfaf, v108
	v_ashrrev_i32_e32 v119, 12, v108
	s_movk_i32 s0, 0xf7f
	s_mov_b64 s[30:31], -1
	s_and_b64 vcc, exec, s[4:5]
	v_cmp_lt_u32_e64 s[0:1], s0, v116
	v_lshlrev_b32_e32 v117, 10, v119
	v_lshlrev_b32_e32 v118, 3, v116
	s_cbranch_vccnz .LBB0_364
	v_lshlrev_b32_e32 v146, 7, v116
	v_lshl_add_u64 v[96:97], s[6:7], 0, v[146:147]
	v_mov_b32_e32 v137, v147
	v_lshl_add_u64 v[98:99], s[12:13], 0, v[146:147]
	v_lshl_add_u64 v[114:115], v[96:97], 0, v[136:137]
	v_lshl_add_u64 v[112:113], v[98:99], 0, v[136:137]
	s_waitcnt lgkmcnt(1)
	v_ashrrev_i32_e32 v109, 31, v108
	v_lshlrev_b64 v[100:101], 12, v[108:109]
	s_waitcnt lgkmcnt(0)
	v_pk_mul_f32 v[110:111], v[84:85], v[104:105] op_sel_hi:[1,0]
	v_lshl_add_u64 v[106:107], v[140:141], 0, v[100:101]
	v_pk_mul_f32 v[102:103], v[92:93], v[104:105] op_sel_hi:[1,0]
	s_and_b64 vcc, exec, s[2:3]
	s_waitcnt vmcnt(6)
	v_mov_b32_e32 v96, v214
	v_mov_b32_e32 v97, v215
	v_mov_b32_e32 v98, v216
	v_mov_b32_e32 v99, v217
	v_mov_b32_e32 v120, v218
	v_mov_b32_e32 v121, v219
	v_mov_b32_e32 v122, v220
	v_mov_b32_e32 v123, v221
	v_add_u32_e32 v251, 0x2000, v250
	global_load_dwordx4 v[214:217], v251, s[6:7] offset:0
	global_load_dwordx4 v[218:221], v251, s[12:13] offset:0
	v_pk_mul_f32 v[100:101], v[110:111], v[120:121]
	s_nop 0
	v_pk_fma_f32 v[100:101], v[102:103], v[96:97], v[100:101] neg_lo:[0,0,1] neg_hi:[0,0,1]
	v_pk_mul_f32 v[102:103], v[102:103], v[120:121]
	v_pk_mul_f32 v[120:121], v[86:87], v[104:105] op_sel_hi:[1,0]
	v_pk_fma_f32 v[96:97], v[110:111], v[96:97], v[102:103]
	v_pk_mul_f32 v[110:111], v[94:95], v[104:105] op_sel_hi:[1,0]
	v_pk_mul_f32 v[102:103], v[120:121], v[122:123]
	s_nop 0
	v_pk_fma_f32 v[102:103], v[110:111], v[98:99], v[102:103] neg_lo:[0,0,1] neg_hi:[0,0,1]
	v_pk_mul_f32 v[110:111], v[110:111], v[122:123]
	s_nop 0
	v_pk_fma_f32 v[98:99], v[120:121], v[98:99], v[110:111]
	s_cbranch_vccnz .LBB0_353
	s_mov_b32 s30, 0x3e000000
	v_lshlrev_b32_e32 v146, 1, v145
	v_pk_mul_f32 v[120:121], v[100:101], s[30:31] op_sel_hi:[1,0]
	v_pk_mul_f32 v[122:123], v[102:103], s[30:31] op_sel_hi:[1,0]
	v_lshl_add_u64 v[110:111], v[106:107], 0, v[146:147]
	v_cvt_pk_bf16_f32 v120, v120, v121
	v_cvt_pk_bf16_f32 v121, v122, v123
	global_store_dwordx2 v[110:111], v[120:121], off
	v_pk_mul_f32 v[120:121], v[96:97], s[30:31] op_sel_hi:[1,0]
	v_pk_mul_f32 v[122:123], v[98:99], s[30:31] op_sel_hi:[1,0]
	v_cvt_pk_bf16_f32 v120, v120, v121
	v_cvt_pk_bf16_f32 v121, v122, v123
	s_mov_b64 s[30:31], 0
	global_store_dwordx2 v[110:111], v[120:121], off offset:64

.LBB0_357:
	s_nop 0
	v_mov_b32_e32 v105, v104
	v_pk_mul_f32 v[120:121], v[80:81], v[104:105]
	v_pk_mul_f32 v[102:103], v[88:89], v[104:105]
	s_mov_b64 s[30:31], -1
	s_and_b64 vcc, exec, s[2:3]
	s_waitcnt vmcnt(6)
	v_mov_b32_e32 v96, v222
	v_mov_b32_e32 v97, v223
	v_mov_b32_e32 v98, v224
	v_mov_b32_e32 v99, v225
	v_mov_b32_e32 v112, v226
	v_mov_b32_e32 v113, v227
	v_mov_b32_e32 v114, v228
	v_mov_b32_e32 v115, v229
	v_add_u32_e32 v251, 0x2000, v250
	global_load_dwordx4 v[222:225], v251, s[6:7] offset:64
	global_load_dwordx4 v[226:229], v251, s[12:13] offset:64
	v_pk_mul_f32 v[100:101], v[120:121], v[112:113]
	s_nop 0
	v_pk_fma_f32 v[100:101], v[102:103], v[96:97], v[100:101] neg_lo:[0,0,1] neg_hi:[0,0,1]
	v_pk_mul_f32 v[102:103], v[102:103], v[112:113]
	v_pk_mul_f32 v[112:113], v[90:91], v[104:105]
	v_pk_fma_f32 v[96:97], v[120:121], v[96:97], v[102:103]
	v_pk_mul_f32 v[120:121], v[82:83], v[104:105]
	s_nop 0
	v_pk_mul_f32 v[102:103], v[120:121], v[114:115]
	s_nop 0
	v_pk_fma_f32 v[102:103], v[112:113], v[98:99], v[102:103] neg_lo:[0,0,1] neg_hi:[0,0,1]
	v_pk_mul_f32 v[112:113], v[112:113], v[114:115]
	s_nop 0
	v_pk_fma_f32 v[98:99], v[120:121], v[98:99], v[112:113]
	s_cbranch_vccnz .LBB0_359
	s_mov_b32 s30, 0x3e000000
	v_lshlrev_b32_e32 v146, 1, v145
	v_pk_mul_f32 v[112:113], v[100:101], s[30:31] op_sel_hi:[1,0]
	v_pk_mul_f32 v[114:115], v[102:103], s[30:31] op_sel_hi:[1,0]
	v_lshl_add_u64 v[106:107], v[106:107], 0, v[146:147]
	v_cvt_pk_bf16_f32 v112, v112, v113
	v_cvt_pk_bf16_f32 v113, v114, v115
	global_store_dwordx2 v[106:107], v[112:113], off offset:32
	v_pk_mul_f32 v[112:113], v[96:97], s[30:31] op_sel_hi:[1,0]
	v_pk_mul_f32 v[114:115], v[98:99], s[30:31] op_sel_hi:[1,0]
	v_cvt_pk_bf16_f32 v112, v112, v113
	v_cvt_pk_bf16_f32 v113, v114, v115
	s_mov_b64 s[30:31], 0
	global_store_dwordx2 v[106:107], v[112:113], off offset:96

.LBB0_374:
	ds_read_b32 v88, v162 offset:192
	v_add3_u32 v92, s43, v163, 48
	v_and_b32_e32 v100, 0xfbf, v92
	v_ashrrev_i32_e32 v103, 12, v92
	s_movk_i32 s0, 0xf7f
	s_mov_b64 s[30:31], -1
	s_and_b64 vcc, exec, s[4:5]
	v_cmp_lt_u32_e64 s[0:1], s0, v100
	v_lshlrev_b32_e32 v101, 10, v103
	v_lshlrev_b32_e32 v102, 3, v100
	s_cbranch_vccnz .LBB0_388
	v_lshlrev_b32_e32 v146, 7, v100
	v_lshl_add_u64 v[80:81], s[6:7], 0, v[146:147]
	v_mov_b32_e32 v137, v147
	v_lshl_add_u64 v[82:83], s[12:13], 0, v[146:147]
	v_lshl_add_u64 v[98:99], v[80:81], 0, v[136:137]
	v_lshl_add_u64 v[96:97], v[82:83], 0, v[136:137]
	s_waitcnt lgkmcnt(1)
	v_ashrrev_i32_e32 v93, 31, v92
	v_lshlrev_b64 v[84:85], 12, v[92:93]
	s_waitcnt lgkmcnt(0)
	v_pk_mul_f32 v[94:95], v[68:69], v[88:89] op_sel_hi:[1,0]
	v_lshl_add_u64 v[90:91], v[140:141], 0, v[84:85]
	v_pk_mul_f32 v[86:87], v[76:77], v[88:89] op_sel_hi:[1,0]
	s_and_b64 vcc, exec, s[2:3]
	s_waitcnt vmcnt(6)
	v_mov_b32_e32 v80, v230
	v_mov_b32_e32 v81, v231
	v_mov_b32_e32 v82, v232
	v_mov_b32_e32 v83, v233
	v_mov_b32_e32 v104, v234
	v_mov_b32_e32 v105, v235
	v_mov_b32_e32 v106, v236
	v_mov_b32_e32 v107, v237
	v_add_u32_e32 v251, 0x2800, v250
	global_load_dwordx4 v[230:233], v251, s[6:7] offset:0
	global_load_dwordx4 v[234:237], v251, s[12:13] offset:0
	v_pk_mul_f32 v[84:85], v[94:95], v[104:105]
	s_nop 0
	v_pk_fma_f32 v[84:85], v[86:87], v[80:81], v[84:85] neg_lo:[0,0,1] neg_hi:[0,0,1]
	v_pk_mul_f32 v[86:87], v[86:87], v[104:105]
	v_pk_mul_f32 v[104:105], v[70:71], v[88:89] op_sel_hi:[1,0]
	v_pk_fma_f32 v[80:81], v[94:95], v[80:81], v[86:87]
	v_pk_mul_f32 v[94:95], v[78:79], v[88:89] op_sel_hi:[1,0]
	v_pk_mul_f32 v[86:87], v[104:105], v[106:107]
	s_nop 0
	v_pk_fma_f32 v[86:87], v[94:95], v[82:83], v[86:87] neg_lo:[0,0,1] neg_hi:[0,0,1]
	v_pk_mul_f32 v[94:95], v[94:95], v[106:107]
	s_nop 0
	v_pk_fma_f32 v[82:83], v[104:105], v[82:83], v[94:95]
	s_cbranch_vccnz .LBB0_377
	s_mov_b32 s30, 0x3e000000
	v_lshlrev_b32_e32 v146, 1, v145
	v_pk_mul_f32 v[104:105], v[84:85], s[30:31] op_sel_hi:[1,0]
	v_pk_mul_f32 v[106:107], v[86:87], s[30:31] op_sel_hi:[1,0]
	v_lshl_add_u64 v[94:95], v[90:91], 0, v[146:147]
	v_cvt_pk_bf16_f32 v104, v104, v105
	v_cvt_pk_bf16_f32 v105, v106, v107
	global_store_dwordx2 v[94:95], v[104:105], off
	v_pk_mul_f32 v[104:105], v[80:81], s[30:31] op_sel_hi:[1,0]
	v_pk_mul_f32 v[106:107], v[82:83], s[30:31] op_sel_hi:[1,0]
	v_cvt_pk_bf16_f32 v104, v104, v105
	v_cvt_pk_bf16_f32 v105, v106, v107
	s_mov_b64 s[30:31], 0
	global_store_dwordx2 v[94:95], v[104:105], off offset:64

.LBB0_381:
	s_nop 0
	v_mov_b32_e32 v89, v88
	v_pk_mul_f32 v[104:105], v[64:65], v[88:89]
	v_pk_mul_f32 v[86:87], v[72:73], v[88:89]
	s_mov_b64 s[30:31], -1
	s_and_b64 vcc, exec, s[2:3]
	s_waitcnt vmcnt(6)
	v_mov_b32_e32 v80, v238
	v_mov_b32_e32 v81, v239
	v_mov_b32_e32 v82, v240
	v_mov_b32_e32 v83, v241
	v_mov_b32_e32 v96, v242
	v_mov_b32_e32 v97, v243
	v_mov_b32_e32 v98, v244
	v_mov_b32_e32 v99, v245
	v_add_u32_e32 v251, 0x2800, v250
	global_load_dwordx4 v[238:241], v251, s[6:7] offset:64
	global_load_dwordx4 v[242:245], v251, s[12:13] offset:64
	v_pk_mul_f32 v[84:85], v[104:105], v[96:97]
	s_nop 0
	v_pk_fma_f32 v[84:85], v[86:87], v[80:81], v[84:85] neg_lo:[0,0,1] neg_hi:[0,0,1]
	v_pk_mul_f32 v[86:87], v[86:87], v[96:97]
	v_pk_mul_f32 v[96:97], v[74:75], v[88:89]
	v_pk_fma_f32 v[80:81], v[104:105], v[80:81], v[86:87]
	v_pk_mul_f32 v[104:105], v[66:67], v[88:89]
	s_nop 0
	v_pk_mul_f32 v[86:87], v[104:105], v[98:99]
	s_nop 0
	v_pk_fma_f32 v[86:87], v[96:97], v[82:83], v[86:87] neg_lo:[0,0,1] neg_hi:[0,0,1]
	v_pk_mul_f32 v[96:97], v[96:97], v[98:99]
	s_nop 0
	v_pk_fma_f32 v[82:83], v[104:105], v[82:83], v[96:97]
	s_cbranch_vccnz .LBB0_383
	s_mov_b32 s30, 0x3e000000
	v_lshlrev_b32_e32 v146, 1, v145
	v_pk_mul_f32 v[96:97], v[84:85], s[30:31] op_sel_hi:[1,0]
	v_pk_mul_f32 v[98:99], v[86:87], s[30:31] op_sel_hi:[1,0]
	v_lshl_add_u64 v[90:91], v[90:91], 0, v[146:147]
	v_cvt_pk_bf16_f32 v96, v96, v97
	v_cvt_pk_bf16_f32 v97, v98, v99
	global_store_dwordx2 v[90:91], v[96:97], off offset:32
	v_pk_mul_f32 v[96:97], v[80:81], s[30:31] op_sel_hi:[1,0]
	v_pk_mul_f32 v[98:99], v[82:83], s[30:31] op_sel_hi:[1,0]
	v_cvt_pk_bf16_f32 v96, v96, v97
	v_cvt_pk_bf16_f32 v97, v98, v99
	s_mov_b64 s[30:31], 0
	global_store_dwordx2 v[90:91], v[96:97], off offset:96

.LBB0_398:
	ds_read_b32 v72, v162 offset:256
	v_add3_u32 v76, s43, v163, 64
	v_and_b32_e32 v84, 0xfcf, v76
	v_ashrrev_i32_e32 v87, 12, v76
	s_movk_i32 s0, 0xf7f
	s_mov_b64 s[30:31], -1
	s_and_b64 vcc, exec, s[4:5]
	v_cmp_lt_u32_e64 s[0:1], s0, v84
	v_lshlrev_b32_e32 v85, 10, v87
	v_lshlrev_b32_e32 v86, 3, v84
	s_cbranch_vccnz .LBB0_412
	v_lshlrev_b32_e32 v146, 7, v84
	v_lshl_add_u64 v[64:65], s[6:7], 0, v[146:147]
	v_mov_b32_e32 v137, v147
	v_lshl_add_u64 v[66:67], s[12:13], 0, v[146:147]
	v_lshl_add_u64 v[82:83], v[64:65], 0, v[136:137]
	v_lshl_add_u64 v[80:81], v[66:67], 0, v[136:137]
	s_waitcnt lgkmcnt(1)
	v_ashrrev_i32_e32 v77, 31, v76
	v_lshlrev_b64 v[68:69], 12, v[76:77]
	s_waitcnt lgkmcnt(0)
	v_pk_mul_f32 v[78:79], v[52:53], v[72:73] op_sel_hi:[1,0]
	v_lshl_add_u64 v[74:75], v[140:141], 0, v[68:69]
	v_pk_mul_f32 v[70:71], v[60:61], v[72:73] op_sel_hi:[1,0]
	s_and_b64 vcc, exec, s[2:3]
	s_waitcnt vmcnt(6)
	v_mov_b32_e32 v64, v214
	v_mov_b32_e32 v65, v215
	v_mov_b32_e32 v66, v216
	v_mov_b32_e32 v67, v217
	v_mov_b32_e32 v88, v218
	v_mov_b32_e32 v89, v219
	v_mov_b32_e32 v90, v220
	v_mov_b32_e32 v91, v221
	v_add_u32_e32 v251, 0x3000, v250
	global_load_dwordx4 v[214:217], v251, s[6:7] offset:0
	global_load_dwordx4 v[218:221], v251, s[12:13] offset:0
	v_pk_mul_f32 v[68:69], v[78:79], v[88:89]
	s_nop 0
	v_pk_fma_f32 v[68:69], v[70:71], v[64:65], v[68:69] neg_lo:[0,0,1] neg_hi:[0,0,1]
	v_pk_mul_f32 v[70:71], v[70:71], v[88:89]
	v_pk_mul_f32 v[88:89], v[54:55], v[72:73] op_sel_hi:[1,0]
	v_pk_fma_f32 v[64:65], v[78:79], v[64:65], v[70:71]
	v_pk_mul_f32 v[78:79], v[62:63], v[72:73] op_sel_hi:[1,0]
	v_pk_mul_f32 v[70:71], v[88:89], v[90:91]
	s_nop 0
	v_pk_fma_f32 v[70:71], v[78:79], v[66:67], v[70:71] neg_lo:[0,0,1] neg_hi:[0,0,1]
	v_pk_mul_f32 v[78:79], v[78:79], v[90:91]
	s_nop 0
	v_pk_fma_f32 v[66:67], v[88:89], v[66:67], v[78:79]
	s_cbranch_vccnz .LBB0_401
	s_mov_b32 s30, 0x3e000000
	v_lshlrev_b32_e32 v146, 1, v145
	v_pk_mul_f32 v[88:89], v[68:69], s[30:31] op_sel_hi:[1,0]
	v_pk_mul_f32 v[90:91], v[70:71], s[30:31] op_sel_hi:[1,0]
	v_lshl_add_u64 v[78:79], v[74:75], 0, v[146:147]
	v_cvt_pk_bf16_f32 v88, v88, v89
	v_cvt_pk_bf16_f32 v89, v90, v91
	global_store_dwordx2 v[78:79], v[88:89], off
	v_pk_mul_f32 v[88:89], v[64:65], s[30:31] op_sel_hi:[1,0]
	v_pk_mul_f32 v[90:91], v[66:67], s[30:31] op_sel_hi:[1,0]
	v_cvt_pk_bf16_f32 v88, v88, v89
	v_cvt_pk_bf16_f32 v89, v90, v91
	s_mov_b64 s[30:31], 0
	global_store_dwordx2 v[78:79], v[88:89], off offset:64

.LBB0_405:
	s_nop 0
	v_mov_b32_e32 v73, v72
	v_pk_mul_f32 v[88:89], v[48:49], v[72:73]
	v_pk_mul_f32 v[70:71], v[56:57], v[72:73]
	s_mov_b64 s[30:31], -1
	s_and_b64 vcc, exec, s[2:3]
	s_waitcnt vmcnt(6)
	v_mov_b32_e32 v64, v222
	v_mov_b32_e32 v65, v223
	v_mov_b32_e32 v66, v224
	v_mov_b32_e32 v67, v225
	v_mov_b32_e32 v80, v226
	v_mov_b32_e32 v81, v227
	v_mov_b32_e32 v82, v228
	v_mov_b32_e32 v83, v229
	v_add_u32_e32 v251, 0x3000, v250
	global_load_dwordx4 v[222:225], v251, s[6:7] offset:64
	global_load_dwordx4 v[226:229], v251, s[12:13] offset:64
	v_pk_mul_f32 v[68:69], v[88:89], v[80:81]
	s_nop 0
	v_pk_fma_f32 v[68:69], v[70:71], v[64:65], v[68:69] neg_lo:[0,0,1] neg_hi:[0,0,1]
	v_pk_mul_f32 v[70:71], v[70:71], v[80:81]
	v_pk_mul_f32 v[80:81], v[58:59], v[72:73]
	v_pk_fma_f32 v[64:65], v[88:89], v[64:65], v[70:71]
	v_pk_mul_f32 v[88:89], v[50:51], v[72:73]
	s_nop 0
	v_pk_mul_f32 v[70:71], v[88:89], v[82:83]
	s_nop 0
	v_pk_fma_f32 v[70:71], v[80:81], v[66:67], v[70:71] neg_lo:[0,0,1] neg_hi:[0,0,1]
	v_pk_mul_f32 v[80:81], v[80:81], v[82:83]
	s_nop 0
	v_pk_fma_f32 v[66:67], v[88:89], v[66:67], v[80:81]
	s_cbranch_vccnz .LBB0_407
	s_mov_b32 s30, 0x3e000000
	v_lshlrev_b32_e32 v146, 1, v145
	v_pk_mul_f32 v[80:81], v[68:69], s[30:31] op_sel_hi:[1,0]
	v_pk_mul_f32 v[82:83], v[70:71], s[30:31] op_sel_hi:[1,0]
	v_lshl_add_u64 v[74:75], v[74:75], 0, v[146:147]
	v_cvt_pk_bf16_f32 v80, v80, v81
	v_cvt_pk_bf16_f32 v81, v82, v83
	global_store_dwordx2 v[74:75], v[80:81], off offset:32
	v_pk_mul_f32 v[80:81], v[64:65], s[30:31] op_sel_hi:[1,0]
	v_pk_mul_f32 v[82:83], v[66:67], s[30:31] op_sel_hi:[1,0]
	v_cvt_pk_bf16_f32 v80, v80, v81
	v_cvt_pk_bf16_f32 v81, v82, v83
	s_mov_b64 s[30:31], 0
	global_store_dwordx2 v[74:75], v[80:81], off offset:96

.LBB0_422:
	ds_read_b32 v56, v162 offset:320
	v_add_u32_e32 v60, 0x50, v142
	v_and_b32_e32 v68, 0xfdf, v60
	v_ashrrev_i32_e32 v71, 12, v60
	s_movk_i32 s0, 0xf7f
	s_mov_b64 s[30:31], -1
	s_and_b64 vcc, exec, s[4:5]
	v_cmp_lt_u32_e64 s[0:1], s0, v68
	v_lshlrev_b32_e32 v69, 10, v71
	v_lshlrev_b32_e32 v70, 3, v68
	s_cbranch_vccnz .LBB0_436
	v_lshlrev_b32_e32 v146, 7, v68
	v_lshl_add_u64 v[48:49], s[6:7], 0, v[146:147]
	v_mov_b32_e32 v137, v147
	v_lshl_add_u64 v[50:51], s[12:13], 0, v[146:147]
	v_lshl_add_u64 v[66:67], v[48:49], 0, v[136:137]
	v_lshl_add_u64 v[64:65], v[50:51], 0, v[136:137]
	s_waitcnt lgkmcnt(1)
	v_ashrrev_i32_e32 v61, 31, v60
	v_lshlrev_b64 v[52:53], 12, v[60:61]
	s_waitcnt lgkmcnt(0)
	v_pk_mul_f32 v[62:63], v[36:37], v[56:57] op_sel_hi:[1,0]
	v_lshl_add_u64 v[58:59], v[140:141], 0, v[52:53]
	v_pk_mul_f32 v[54:55], v[44:45], v[56:57] op_sel_hi:[1,0]
	s_and_b64 vcc, exec, s[2:3]
	s_waitcnt vmcnt(6)
	v_mov_b32_e32 v48, v230
	v_mov_b32_e32 v49, v231
	v_mov_b32_e32 v50, v232
	v_mov_b32_e32 v51, v233
	v_mov_b32_e32 v72, v234
	v_mov_b32_e32 v73, v235
	v_mov_b32_e32 v74, v236
	v_mov_b32_e32 v75, v237
	v_add_u32_e32 v251, 0x3800, v250
	global_load_dwordx4 v[230:233], v251, s[6:7] offset:0
	global_load_dwordx4 v[234:237], v251, s[12:13] offset:0
	v_pk_mul_f32 v[52:53], v[62:63], v[72:73]
	s_nop 0
	v_pk_fma_f32 v[52:53], v[54:55], v[48:49], v[52:53] neg_lo:[0,0,1] neg_hi:[0,0,1]
	v_pk_mul_f32 v[54:55], v[54:55], v[72:73]
	v_pk_mul_f32 v[72:73], v[38:39], v[56:57] op_sel_hi:[1,0]
	v_pk_fma_f32 v[48:49], v[62:63], v[48:49], v[54:55]
	v_pk_mul_f32 v[62:63], v[46:47], v[56:57] op_sel_hi:[1,0]
	v_pk_mul_f32 v[54:55], v[72:73], v[74:75]
	s_nop 0
	v_pk_fma_f32 v[54:55], v[62:63], v[50:51], v[54:55] neg_lo:[0,0,1] neg_hi:[0,0,1]
	v_pk_mul_f32 v[62:63], v[62:63], v[74:75]
	s_nop 0
	v_pk_fma_f32 v[50:51], v[72:73], v[50:51], v[62:63]
	s_cbranch_vccnz .LBB0_425
	s_mov_b32 s30, 0x3e000000
	v_lshlrev_b32_e32 v146, 1, v145
	v_pk_mul_f32 v[72:73], v[52:53], s[30:31] op_sel_hi:[1,0]
	v_pk_mul_f32 v[74:75], v[54:55], s[30:31] op_sel_hi:[1,0]
	v_lshl_add_u64 v[62:63], v[58:59], 0, v[146:147]
	v_cvt_pk_bf16_f32 v72, v72, v73
	v_cvt_pk_bf16_f32 v73, v74, v75
	global_store_dwordx2 v[62:63], v[72:73], off
	v_pk_mul_f32 v[72:73], v[48:49], s[30:31] op_sel_hi:[1,0]
	v_pk_mul_f32 v[74:75], v[50:51], s[30:31] op_sel_hi:[1,0]
	v_cvt_pk_bf16_f32 v72, v72, v73
	v_cvt_pk_bf16_f32 v73, v74, v75
	s_mov_b64 s[30:31], 0
	global_store_dwordx2 v[62:63], v[72:73], off offset:64

.LBB0_429:
	s_nop 0
	v_mov_b32_e32 v57, v56
	v_pk_mul_f32 v[72:73], v[32:33], v[56:57]
	v_pk_mul_f32 v[54:55], v[40:41], v[56:57]
	s_mov_b64 s[30:31], -1
	s_and_b64 vcc, exec, s[2:3]
	s_waitcnt vmcnt(6)
	v_mov_b32_e32 v48, v238
	v_mov_b32_e32 v49, v239
	v_mov_b32_e32 v50, v240
	v_mov_b32_e32 v51, v241
	v_mov_b32_e32 v64, v242
	v_mov_b32_e32 v65, v243
	v_mov_b32_e32 v66, v244
	v_mov_b32_e32 v67, v245
	v_add_u32_e32 v251, 0x3800, v250
	global_load_dwordx4 v[238:241], v251, s[6:7] offset:64
	global_load_dwordx4 v[242:245], v251, s[12:13] offset:64
	v_pk_mul_f32 v[52:53], v[72:73], v[64:65]
	s_nop 0
	v_pk_fma_f32 v[52:53], v[54:55], v[48:49], v[52:53] neg_lo:[0,0,1] neg_hi:[0,0,1]
	v_pk_mul_f32 v[54:55], v[54:55], v[64:65]
	v_pk_mul_f32 v[64:65], v[42:43], v[56:57]
	v_pk_fma_f32 v[48:49], v[72:73], v[48:49], v[54:55]
	v_pk_mul_f32 v[72:73], v[34:35], v[56:57]
	s_nop 0
	v_pk_mul_f32 v[54:55], v[72:73], v[66:67]
	s_nop 0
	v_pk_fma_f32 v[54:55], v[64:65], v[50:51], v[54:55] neg_lo:[0,0,1] neg_hi:[0,0,1]
	v_pk_mul_f32 v[64:65], v[64:65], v[66:67]
	s_nop 0
	v_pk_fma_f32 v[50:51], v[72:73], v[50:51], v[64:65]
	s_cbranch_vccnz .LBB0_431
	s_mov_b32 s30, 0x3e000000
	v_lshlrev_b32_e32 v146, 1, v145
	v_pk_mul_f32 v[64:65], v[52:53], s[30:31] op_sel_hi:[1,0]
	v_pk_mul_f32 v[66:67], v[54:55], s[30:31] op_sel_hi:[1,0]
	v_lshl_add_u64 v[58:59], v[58:59], 0, v[146:147]
	v_cvt_pk_bf16_f32 v64, v64, v65
	v_cvt_pk_bf16_f32 v65, v66, v67
	global_store_dwordx2 v[58:59], v[64:65], off offset:32
	v_pk_mul_f32 v[64:65], v[48:49], s[30:31] op_sel_hi:[1,0]
	v_pk_mul_f32 v[66:67], v[50:51], s[30:31] op_sel_hi:[1,0]
	v_cvt_pk_bf16_f32 v64, v64, v65
	v_cvt_pk_bf16_f32 v65, v66, v67
	s_mov_b64 s[30:31], 0
	global_store_dwordx2 v[58:59], v[64:65], off offset:96

.LBB0_446:
	ds_read_b32 v40, v162 offset:384
	v_add_u32_e32 v44, 0x60, v142
	v_and_b32_e32 v52, 0xfef, v44
	v_ashrrev_i32_e32 v55, 12, v44
	s_movk_i32 s0, 0xf7f
	s_mov_b64 s[30:31], -1
	s_and_b64 vcc, exec, s[4:5]
	v_cmp_lt_u32_e64 s[0:1], s0, v52
	v_lshlrev_b32_e32 v53, 10, v55
	v_lshlrev_b32_e32 v54, 3, v52
	s_cbranch_vccnz .LBB0_460
	v_lshlrev_b32_e32 v146, 7, v52
	v_lshl_add_u64 v[32:33], s[6:7], 0, v[146:147]
	v_mov_b32_e32 v137, v147
	v_lshl_add_u64 v[34:35], s[12:13], 0, v[146:147]
	v_lshl_add_u64 v[50:51], v[32:33], 0, v[136:137]
	v_lshl_add_u64 v[48:49], v[34:35], 0, v[136:137]
	s_waitcnt lgkmcnt(1)
	v_ashrrev_i32_e32 v45, 31, v44
	v_lshlrev_b64 v[36:37], 12, v[44:45]
	s_waitcnt lgkmcnt(0)
	v_pk_mul_f32 v[46:47], v[20:21], v[40:41] op_sel_hi:[1,0]
	v_lshl_add_u64 v[42:43], v[140:141], 0, v[36:37]
	v_pk_mul_f32 v[38:39], v[28:29], v[40:41] op_sel_hi:[1,0]
	s_and_b64 vcc, exec, s[2:3]
	s_waitcnt vmcnt(6)
	v_mov_b32_e32 v32, v214
	v_mov_b32_e32 v33, v215
	v_mov_b32_e32 v34, v216
	v_mov_b32_e32 v35, v217
	v_mov_b32_e32 v56, v218
	v_mov_b32_e32 v57, v219
	v_mov_b32_e32 v58, v220
	v_mov_b32_e32 v59, v221
	v_pk_mul_f32 v[36:37], v[46:47], v[56:57]
	s_nop 0
	v_pk_fma_f32 v[36:37], v[38:39], v[32:33], v[36:37] neg_lo:[0,0,1] neg_hi:[0,0,1]
	v_pk_mul_f32 v[38:39], v[38:39], v[56:57]
	v_pk_mul_f32 v[56:57], v[22:23], v[40:41] op_sel_hi:[1,0]
	v_pk_fma_f32 v[32:33], v[46:47], v[32:33], v[38:39]
	v_pk_mul_f32 v[46:47], v[30:31], v[40:41] op_sel_hi:[1,0]
	v_pk_mul_f32 v[38:39], v[56:57], v[58:59]
	s_nop 0
	v_pk_fma_f32 v[38:39], v[46:47], v[34:35], v[38:39] neg_lo:[0,0,1] neg_hi:[0,0,1]
	v_pk_mul_f32 v[46:47], v[46:47], v[58:59]
	s_nop 0
	v_pk_fma_f32 v[34:35], v[56:57], v[34:35], v[46:47]
	s_cbranch_vccnz .LBB0_449
	s_mov_b32 s30, 0x3e000000
	v_lshlrev_b32_e32 v146, 1, v145
	v_pk_mul_f32 v[56:57], v[36:37], s[30:31] op_sel_hi:[1,0]
	v_pk_mul_f32 v[58:59], v[38:39], s[30:31] op_sel_hi:[1,0]
	v_lshl_add_u64 v[46:47], v[42:43], 0, v[146:147]
	v_cvt_pk_bf16_f32 v56, v56, v57
	v_cvt_pk_bf16_f32 v57, v58, v59
	global_store_dwordx2 v[46:47], v[56:57], off
	v_pk_mul_f32 v[56:57], v[32:33], s[30:31] op_sel_hi:[1,0]
	v_pk_mul_f32 v[58:59], v[34:35], s[30:31] op_sel_hi:[1,0]
	v_cvt_pk_bf16_f32 v56, v56, v57
	v_cvt_pk_bf16_f32 v57, v58, v59
	s_mov_b64 s[30:31], 0
	global_store_dwordx2 v[46:47], v[56:57], off offset:64

.LBB0_453:
	s_nop 0
	v_mov_b32_e32 v41, v40
	v_pk_mul_f32 v[56:57], v[16:17], v[40:41]
	v_pk_mul_f32 v[38:39], v[24:25], v[40:41]
	s_mov_b64 s[30:31], -1
	s_and_b64 vcc, exec, s[2:3]
	s_waitcnt vmcnt(4)
	v_mov_b32_e32 v32, v222
	v_mov_b32_e32 v33, v223
	v_mov_b32_e32 v34, v224
	v_mov_b32_e32 v35, v225
	v_mov_b32_e32 v48, v226
	v_mov_b32_e32 v49, v227
	v_mov_b32_e32 v50, v228
	v_mov_b32_e32 v51, v229
	v_pk_mul_f32 v[36:37], v[56:57], v[48:49]
	s_nop 0
	v_pk_fma_f32 v[36:37], v[38:39], v[32:33], v[36:37] neg_lo:[0,0,1] neg_hi:[0,0,1]
	v_pk_mul_f32 v[38:39], v[38:39], v[48:49]
	v_pk_mul_f32 v[48:49], v[26:27], v[40:41]
	v_pk_fma_f32 v[32:33], v[56:57], v[32:33], v[38:39]
	v_pk_mul_f32 v[56:57], v[18:19], v[40:41]
	s_nop 0
	v_pk_mul_f32 v[38:39], v[56:57], v[50:51]
	s_nop 0
	v_pk_fma_f32 v[38:39], v[48:49], v[34:35], v[38:39] neg_lo:[0,0,1] neg_hi:[0,0,1]
	v_pk_mul_f32 v[48:49], v[48:49], v[50:51]
	s_nop 0
	v_pk_fma_f32 v[34:35], v[56:57], v[34:35], v[48:49]
	s_cbranch_vccnz .LBB0_455
	s_mov_b32 s30, 0x3e000000
	v_lshlrev_b32_e32 v146, 1, v145
	v_pk_mul_f32 v[48:49], v[36:37], s[30:31] op_sel_hi:[1,0]
	v_pk_mul_f32 v[50:51], v[38:39], s[30:31] op_sel_hi:[1,0]
	v_lshl_add_u64 v[42:43], v[42:43], 0, v[146:147]
	v_cvt_pk_bf16_f32 v48, v48, v49
	v_cvt_pk_bf16_f32 v49, v50, v51
	global_store_dwordx2 v[42:43], v[48:49], off offset:32
	v_pk_mul_f32 v[48:49], v[32:33], s[30:31] op_sel_hi:[1,0]
	v_pk_mul_f32 v[50:51], v[34:35], s[30:31] op_sel_hi:[1,0]
	v_cvt_pk_bf16_f32 v48, v48, v49
	v_cvt_pk_bf16_f32 v49, v50, v51
	s_mov_b64 s[30:31], 0
	global_store_dwordx2 v[42:43], v[48:49], off offset:96

.LBB0_470:
	ds_read_b32 v24, v162 offset:448
	v_add_u32_e32 v32, 0x70, v142
	v_and_b32_e32 v36, 0xfff, v32
	v_ashrrev_i32_e32 v39, 12, v32
	s_movk_i32 s0, 0xf7f
	s_mov_b64 s[30:31], -1
	s_and_b64 vcc, exec, s[4:5]
	v_cmp_lt_u32_e64 s[0:1], s0, v36
	v_lshlrev_b32_e32 v37, 10, v39
	v_lshlrev_b32_e32 v38, 3, v36
	s_cbranch_vccnz .LBB0_484
	v_lshlrev_b32_e32 v146, 7, v36
	v_lshl_add_u64 v[16:17], s[6:7], 0, v[146:147]
	v_mov_b32_e32 v137, v147
	v_lshl_add_u64 v[18:19], s[12:13], 0, v[146:147]
	v_lshl_add_u64 v[28:29], v[16:17], 0, v[136:137]
	v_lshl_add_u64 v[30:31], v[18:19], 0, v[136:137]
	s_waitcnt lgkmcnt(1)
	v_ashrrev_i32_e32 v33, 31, v32
	v_lshlrev_b64 v[20:21], 12, v[32:33]
	s_waitcnt lgkmcnt(0)
	v_pk_mul_f32 v[34:35], v[4:5], v[24:25] op_sel_hi:[1,0]
	v_lshl_add_u64 v[26:27], v[140:141], 0, v[20:21]
	v_pk_mul_f32 v[22:23], v[12:13], v[24:25] op_sel_hi:[1,0]
	s_mov_b64 s[4:5], -1
	s_and_b64 vcc, exec, s[2:3]
	v_lshlrev_b32_e32 v146, 1, v145
	s_waitcnt vmcnt(2)
	v_mov_b32_e32 v16, v230
	v_mov_b32_e32 v17, v231
	v_mov_b32_e32 v18, v232
	v_mov_b32_e32 v19, v233
	v_mov_b32_e32 v40, v234
	v_mov_b32_e32 v41, v235
	v_mov_b32_e32 v42, v236
	v_mov_b32_e32 v43, v237
	v_pk_mul_f32 v[20:21], v[34:35], v[40:41]
	s_nop 0
	v_pk_fma_f32 v[20:21], v[22:23], v[16:17], v[20:21] neg_lo:[0,0,1] neg_hi:[0,0,1]
	v_pk_mul_f32 v[22:23], v[22:23], v[40:41]
	v_pk_mul_f32 v[40:41], v[6:7], v[24:25] op_sel_hi:[1,0]
	v_pk_fma_f32 v[16:17], v[34:35], v[16:17], v[22:23]
	v_pk_mul_f32 v[34:35], v[14:15], v[24:25] op_sel_hi:[1,0]
	v_pk_mul_f32 v[22:23], v[40:41], v[42:43]
	s_nop 0
	v_pk_fma_f32 v[22:23], v[34:35], v[18:19], v[22:23] neg_lo:[0,0,1] neg_hi:[0,0,1]
	v_pk_mul_f32 v[34:35], v[34:35], v[42:43]
	s_nop 0
	v_pk_fma_f32 v[18:19], v[40:41], v[18:19], v[34:35]
	s_cbranch_vccnz .LBB0_473
	s_mov_b32 s4, 0x3e000000
	v_pk_mul_f32 v[40:41], v[20:21], s[4:5] op_sel_hi:[1,0]
	v_pk_mul_f32 v[42:43], v[22:23], s[4:5] op_sel_hi:[1,0]
	v_lshl_add_u64 v[34:35], v[26:27], 0, v[146:147]
	v_cvt_pk_bf16_f32 v40, v40, v41
	v_cvt_pk_bf16_f32 v41, v42, v43
	global_store_dwordx2 v[34:35], v[40:41], off
	v_pk_mul_f32 v[40:41], v[16:17], s[4:5] op_sel_hi:[1,0]
	v_pk_mul_f32 v[42:43], v[18:19], s[4:5] op_sel_hi:[1,0]
	v_cvt_pk_bf16_f32 v40, v40, v41
	v_cvt_pk_bf16_f32 v41, v42, v43
	s_mov_b64 s[4:5], 0
	global_store_dwordx2 v[34:35], v[40:41], off offset:64

.LBB0_477:
	s_nop 0
	v_mov_b32_e32 v25, v24
	v_pk_mul_f32 v[20:21], v[8:9], v[24:25]
	v_pk_mul_f32 v[22:23], v[0:1], v[24:25]
	v_pk_mul_f32 v[40:41], v[10:11], v[24:25]
	v_pk_mul_f32 v[42:43], v[2:3], v[24:25]
	s_and_b64 vcc, exec, s[2:3]
	s_mov_b64 s[2:3], -1
	s_waitcnt vmcnt(0)
	v_mov_b32_e32 v28, v238
	v_mov_b32_e32 v29, v239
	v_mov_b32_e32 v30, v240
	v_mov_b32_e32 v31, v241
	v_mov_b32_e32 v16, v242
	v_mov_b32_e32 v17, v243
	v_mov_b32_e32 v18, v244
	v_mov_b32_e32 v19, v245
	v_pk_mul_f32 v[44:45], v[22:23], v[16:17]
	v_pk_mul_f32 v[16:17], v[20:21], v[16:17]
	v_pk_mul_f32 v[46:47], v[42:43], v[18:19]
	v_pk_mul_f32 v[18:19], v[40:41], v[18:19]
	v_pk_fma_f32 v[20:21], v[20:21], v[28:29], v[44:45] neg_lo:[0,0,1] neg_hi:[0,0,1]
	v_pk_fma_f32 v[16:17], v[22:23], v[28:29], v[16:17]
	v_pk_fma_f32 v[22:23], v[40:41], v[30:31], v[46:47] neg_lo:[0,0,1] neg_hi:[0,0,1]
	v_pk_fma_f32 v[18:19], v[42:43], v[30:31], v[18:19]
	s_cbranch_vccnz .LBB0_479
	s_mov_b32 s2, 0x3e000000
	v_pk_mul_f32 v[28:29], v[20:21], s[2:3] op_sel_hi:[1,0]
	v_pk_mul_f32 v[30:31], v[22:23], s[2:3] op_sel_hi:[1,0]
	v_lshl_add_u64 v[26:27], v[26:27], 0, v[146:147]
	v_cvt_pk_bf16_f32 v28, v28, v29
	v_cvt_pk_bf16_f32 v29, v30, v31
	global_store_dwordx2 v[26:27], v[28:29], off offset:32
	v_pk_mul_f32 v[28:29], v[16:17], s[2:3] op_sel_hi:[1,0]
	v_pk_mul_f32 v[30:31], v[18:19], s[2:3] op_sel_hi:[1,0]
	v_cvt_pk_bf16_f32 v28, v28, v29
	v_cvt_pk_bf16_f32 v29, v30, v31
	s_mov_b64 s[2:3], 0
	global_store_dwordx2 v[26:27], v[28:29], off offset:96
